# v11 + final-phase (rmsnorm/residual) loop: hoisted loop-invariant norm weight loads, merged token loads into one wait
# baseline (speedup 1.0000x reference)
; DEVI int tidx() { int t = threadIdx.x; asm volatile("" : "+v"(t)); return t; }
; DEVI int bidx() { int b = blockIdx.x; asm volatile("" : "+s"(b)); return b; }
; DEVI float bf2f(bf16_t h) { return __uint_as_float(((unsigned)h) << 16); }
; DEVI unsigned pack2(float a, float b) { f2_t v = {a, b}; bf2_t r = __builtin_convertvector(v, bf2_t); return __builtin_bit_cast(unsigned, r); }
; DEVI void phase_final(const Params& p, int layer) {
;   const int lane = tidx() & 63;
;   const int gw = (bidx() * blockDim.x + tidx()) >> 6, nw = (gridDim.x * blockDim.x) >> 6;
;   const float* Y = (const float*)(p.ws + RP_OFF);
;   bf16_t* n0 = (bf16_t*)p.out;
;   bf16_t* xb = (bf16_t*)((unsigned char*)p.out + XB_OFF);
;   const bf16_t* n0c = (const bf16_t*)(p.ws + RP_OFF + 320 * MiB);
;   const float* gpost = p.norm_post + layer * 1024;
;   for (int t = gw; t < NTOK; t += nw) {
;     const float* x = xrow0(p, t);
;     float4 y[4], xv[4]; float ss = 0.f;
; #pragma unroll
;     for (int i = 0; i < 4; ++i) {
;       y[i] = *(const float4*)(Y + (size_t)t * 1024 + i * 256 + lane * 4);
;       xv[i] = *(const float4*)(x + i * 256 + lane * 4);
;       ss += y[i].x * y[i].x + y[i].y * y[i].y + y[i].z * y[i].z + y[i].w * y[i].w;
;     }
;     ss = wave_sum(ss);
;     const float rs = rsqrtf(ss * (1.f / 1024.f) + 1e-6f);
;     if (layer == 0) {
;       float ss1 = 0.f;
; #pragma unroll
;       for (int i = 0; i < 4; ++i) {
;         const float4 g = *(const float4*)(gpost + i * 256 + lane * 4);
;         uint2 o; o.x = pack2(y[i].x * rs * g.x, y[i].y * rs * g.y); o.y = pack2(y[i].z * rs * g.z, y[i].w * rs * g.w);
;         *(uint2*)(n0 + (size_t)t * 1024 + i * 256 + lane * 4) = o;
;         xv[i].x += bf2f((bf16_t)(o.x & 0xffff)); xv[i].y += bf2f((bf16_t)(o.x >> 16));
;         xv[i].z += bf2f((bf16_t)(o.y & 0xffff)); xv[i].w += bf2f((bf16_t)(o.y >> 16));
;         ss1 += xv[i].x * xv[i].x + xv[i].y * xv[i].y + xv[i].z * xv[i].z + xv[i].w * xv[i].w;
;       }
;       ss1 = wave_sum(ss1);
;       const float rs1 = rsqrtf(ss1 * (1.f / 1024.f) + 1e-6f);
; #pragma unroll
;       for (int i = 0; i < 4; ++i) {
;         const float4 g = *(const float4*)(p.norm_pre + 1024 + i * 256 + lane * 4);
.LBB0_1397:
	v_readlane_b32 s2, v251, 3
	v_readlane_b32 s20, v250, 47
	v_readlane_b32 s3, v251, 4
	v_readlane_b32 s21, v250, 48
	v_mov_b32_e32 v2, v197
	v_readlane_b32 s0, v251, 0
	v_readlane_b32 s1, v250, 33
	v_mov_b32_e32 v0, v197
	s_mul_i32 s0, s0, s1
	s_nop 0
	v_add_u32_e32 v0, s0, v0
	v_cmp_gt_u32_e32 vcc, s4, v0
	s_and_saveexec_b64 s[0:1], vcc
	s_cbranch_execz .LBB0_1404
	v_lshrrev_b32_e32 v64, 6, v0
	v_lshlrev_b32_e32 v0, 2, v2
	v_cmp_lt_i32_e32 vcc, v217, v216
	v_and_b32_e32 v4, 0xfc, v0
	s_lshl_b32 s84, s64, 10
	v_cndmask_b32_e32 v0, v215, v217, vcc
	v_cmp_lt_i32_e32 vcc, v218, v216
	v_lshlrev_b32_e32 v65, 2, v0
	v_readlane_b32 s52, v251, 17
	v_cndmask_b32_e32 v0, v215, v218, vcc
	v_cmp_lt_i32_e32 vcc, v219, v216
	v_lshlrev_b32_e32 v66, 2, v0
	s_lshl_b64 s[22:23], s[84:85], 2
	v_cndmask_b32_e32 v0, v215, v219, vcc
	v_cmp_lt_i32_e32 vcc, v220, v216
	v_lshlrev_b32_e32 v67, 2, v0
	v_readlane_b32 s58, v251, 23
	v_cndmask_b32_e32 v0, v215, v220, vcc
	v_cmp_lt_i32_e32 vcc, v221, v216
	v_lshlrev_b32_e32 v68, 2, v0
	v_readlane_b32 s59, v251, 24
	v_cndmask_b32_e32 v0, v215, v221, vcc
	v_cmp_lt_i32_e32 vcc, v222, v216
	s_add_u32 s22, s58, s22
	v_lshlrev_b32_e32 v69, 2, v0
	v_cndmask_b32_e32 v0, v215, v222, vcc
	s_addc_u32 s23, s59, s23
	v_lshlrev_b32_e32 v70, 2, v0
	v_lshlrev_b32_e32 v0, 2, v4
	v_lshl_add_u64 v[38:39], s[22:23], 0, v[0:1]
	v_readlane_b32 s22, v251, 11
	v_readlane_b32 s23, v251, 12
	v_lshl_add_u64 v[50:51], s[20:21], 0, v[0:1]
	v_and_b32_e32 v5, 63, v2
	v_lshl_add_u64 v[42:43], s[22:23], 0, v[0:1]
	v_readlane_b32 s22, v251, 13
	v_readlane_b32 s23, v251, 14
	v_lshlrev_b32_e32 v6, 1, v4
	v_mov_b32_e32 v7, v1
	v_lshl_add_u64 v[44:45], s[22:23], 0, v[0:1]
	v_readlane_b32 s22, v251, 15
	v_readlane_b32 s23, v251, 16
	v_lshlrev_b32_e32 v2, 4, v5
	s_waitcnt vmcnt(0)
	v_mov_b32_e32 v3, v1
	v_lshl_add_u64 v[46:47], s[22:23], 0, v[0:1]
	v_readlane_b32 s22, v251, 33
	v_readlane_b32 s23, v251, 34
	v_lshl_add_u64 v[40:41], s[20:21], 0, v[6:7]
	v_lshl_add_u64 v[54:55], s[2:3], 0, v[2:3]
	v_lshl_add_u64 v[48:49], s[22:23], 0, v[0:1]
	v_lshlrev_b32_e32 v0, 10, v64
	v_lshlrev_b64 v[52:53], 2, v[0:1]
	v_lshlrev_b64 v[56:57], 1, v[0:1]
	v_lshlrev_b32_e32 v0, 3, v5
	v_lshl_add_u64 v[58:59], s[2:3], 0, v[0:1]
	s_mov_b64 s[22:23], 0
	v_lshlrev_b32_e32 v60, 2, v4
	v_readlane_b32 s53, v251, 18
	v_readlane_b32 s54, v251, 19
	v_readlane_b32 s55, v251, 20
	v_readlane_b32 s56, v251, 21
	v_readlane_b32 s57, v251, 22
	v_readlane_b32 s60, v251, 25
	v_readlane_b32 s61, v251, 26
	v_readlane_b32 s62, v251, 27
	v_readlane_b32 s63, v251, 28
	v_readlane_b32 s64, v251, 29
	v_readlane_b32 s65, v251, 30
	v_readlane_b32 s66, v251, 31
	v_readlane_b32 s67, v251, 32
	global_load_dwordx4 v[100:103], v[38:39], off
	global_load_dwordx4 v[104:107], v[38:39], off offset:1024
	global_load_dwordx4 v[108:111], v[38:39], off offset:2048
	global_load_dwordx4 v[112:115], v[38:39], off offset:3072
	global_load_dwordx4 v[116:119], v[42:43], off
	global_load_dwordx4 v[120:123], v[44:45], off
	global_load_dwordx4 v[124:127], v[46:47], off
	global_load_dwordx4 v[128:131], v[48:49], off
	s_waitcnt vmcnt(0)
	s_branch .LBB0_1400

; DEVI float bf2f(bf16_t h) { return __uint_as_float(((unsigned)h) << 16); }
; DEVI void phase_final(const Params& p, int layer) {
;     ...
;   for (int t = gw; t < NTOK; t += nw) {
;     const float* x = xrow0(p, t);
;     float4 y[4], xv[4]; float ss = 0.f;
; #pragma unroll
;     for (int i = 0; i < 4; ++i) {
;       y[i] = *(const float4*)(Y + (size_t)t * 1024 + i * 256 + lane * 4);
;       xv[i] = *(const float4*)(x + i * 256 + lane * 4);
;       ss += y[i].x * y[i].x + y[i].y * y[i].y + y[i].z * y[i].z + y[i].w * y[i].w;
;     }
;     ss = wave_sum(ss);
;     const float rs = rsqrtf(ss * (1.f / 1024.f) + 1e-6f);
;     if (layer == 0) {
;       float ss1 = 0.f;
; #pragma unroll
;       for (int i = 0; i < 4; ++i) {
;         const float4 g = *(const float4*)(gpost + i * 256 + lane * 4);
;         uint2 o; o.x = pack2(y[i].x * rs * g.x, y[i].y * rs * g.y); o.y = pack2(y[i].z * rs * g.z, y[i].w * rs * g.w);
;         *(uint2*)(n0 + (size_t)t * 1024 + i * 256 + lane * 4) = o;
;         xv[i].x += bf2f((bf16_t)(o.x & 0xffff)); xv[i].y += bf2f((bf16_t)(o.x >> 16));
;         xv[i].z += bf2f((bf16_t)(o.y & 0xffff)); xv[i].w += bf2f((bf16_t)(o.y >> 16));
;         ss1 += xv[i].x * xv[i].x + xv[i].y * xv[i].y + xv[i].z * xv[i].z + xv[i].w * xv[i].w;
;       }
;       ss1 = wave_sum(ss1);
;       const float rs1 = rsqrtf(ss1 * (1.f / 1024.f) + 1e-6f);
; #pragma unroll
;       for (int i = 0; i < 4; ++i) {
;         const float4 g = *(const float4*)(p.norm_pre + 1024 + i * 256 + lane * 4);
;         uint2 o; o.x = pack2(xv[i].x * rs1 * g.x, xv[i].y * rs1 * g.y); o.y = pack2(xv[i].z * rs1 * g.z, xv[i].w * rs1 * g.w);
;         *(uint2*)(xb + (size_t)t * 1024 + i * 256 + lane * 4) = o;
;       }
;     } else {
; #pragma unroll
;       for (int i = 0; i < 4; ++i) {
;         const float4 g = *(const float4*)(gpost + i * 256 + lane * 4);
;         const uint2 nb = *(const uint2*)(n0c + (size_t)t * 1024 + i * 256 + lane * 4);
;         float4 o;
;         o.x = xv[i].x + bf2f((bf16_t)(nb.x & 0xffff)) + y[i].x * rs * g.x;
;         o.y = xv[i].y + bf2f((bf16_t)(nb.x >> 16)) + y[i].y * rs * g.y;
;         o.z = xv[i].z + bf2f((bf16_t)(nb.y & 0xffff)) + y[i].z * rs * g.z;
;         o.w = xv[i].w + bf2f((bf16_t)(nb.y >> 16)) + y[i].w * rs * g.w;
;         *(float4*)(p.out + (size_t)t * 1024 + i * 256 + lane * 4) = o;
;       }
.LBB0_1400:
	v_readlane_b32 s52, v251, 17
	v_readlane_b32 s53, v251, 18
	v_readlane_b32 s55, v251, 20
	v_subrev_co_u32_e32 v0, vcc, 0x4000, v64
	v_readlane_b32 s54, v251, 19
	v_mov_b32_e32 v2, s55
	v_mov_b32_e32 v3, s53
	v_cndmask_b32_e32 v0, v0, v64, vcc
	v_cndmask_b32_e32 v3, v2, v3, vcc
	v_mov_b32_e32 v2, s54
	v_mov_b32_e32 v4, s52
	v_cndmask_b32_e32 v2, v2, v4, vcc
	v_lshlrev_b64 v[4:5], 12, v[0:1]
	v_lshl_add_u64 v[2:3], v[2:3], 0, v[4:5]
	v_lshl_add_u64 v[4:5], v[54:55], 0, v[52:53]
	v_mov_b32_e32 v61, v1
	v_add_co_u32_e32 v30, vcc, s15, v4
	v_lshl_add_u64 v[6:7], v[2:3], 0, v[60:61]
	s_nop 0
	v_addc_co_u32_e32 v31, vcc, 0, v5, vcc
	global_load_dwordx4 v[10:13], v[6:7], off
	global_load_dwordx4 v[26:29], v[30:31], off offset:1024
	global_load_dwordx4 v[14:17], v[6:7], off offset:1024
	global_load_dwordx4 v[22:25], v[30:31], off offset:2048
	global_load_dwordx4 v[2:5], v[6:7], off offset:2048
	global_load_dwordx4 v[18:21], v[30:31], off offset:3072
	s_nop 0
	global_load_dwordx4 v[6:9], v[6:7], off offset:3072
	global_load_dwordx4 v[84:87], v[30:31], off
	v_readlane_b32 s16, v249, 40
	v_readlane_b32 s17, v249, 41
	s_mov_b64 s[2:3], -1
	v_readlane_b32 s56, v251, 21
	v_readlane_b32 s57, v251, 22
	v_readlane_b32 s58, v251, 23
	v_readlane_b32 s59, v251, 24
	v_readlane_b32 s60, v251, 25
	v_readlane_b32 s61, v251, 26
	v_readlane_b32 s62, v251, 27
	v_readlane_b32 s63, v251, 28
	v_readlane_b32 s64, v251, 29
	v_readlane_b32 s65, v251, 30
	v_readlane_b32 s66, v251, 31
	v_readlane_b32 s67, v251, 32
	s_waitcnt vmcnt(0) lgkmcnt(0)
	v_mov_b32_e32 v75, v27
	v_mov_b32_e32 v73, v26
	v_mov_b32_e32 v34, v23
	v_mov_b32_e32 v32, v22
	v_mov_b32_e32 v35, v19
	v_mov_b32_e32 v33, v18
	v_pk_mul_f32 v[34:35], v[34:35], v[34:35]
	s_nop 0
	v_pk_fma_f32 v[32:33], v[32:33], v[32:33], v[34:35]
	v_mov_b32_e32 v34, v24
	v_mov_b32_e32 v35, v20
	v_pk_fma_f32 v[32:33], v[34:35], v[34:35], v[32:33]
	v_mov_b32_e32 v34, v25
	v_mov_b32_e32 v35, v21
	v_pk_fma_f32 v[62:63], v[34:35], v[34:35], v[32:33]
	v_mov_b32_e32 v30, v84
	v_mov_b32_e32 v31, v85
	v_mov_b32_e32 v32, v86
	v_mov_b32_e32 v33, v87
	s_nop 0
	v_mov_b32_e32 v34, v100
	v_mov_b32_e32 v35, v101
	v_mov_b32_e32 v36, v102
	v_mov_b32_e32 v37, v103
	s_waitcnt vmcnt(0) lgkmcnt(0)
	v_mov_b32_e32 v74, v31
	v_mov_b32_e32 v72, v30
	v_pk_mul_f32 v[74:75], v[74:75], v[74:75]
	s_nop 0
	v_pk_fma_f32 v[72:73], v[72:73], v[72:73], v[74:75]
	v_mov_b32_e32 v74, v32
	v_mov_b32_e32 v75, v28
	v_pk_fma_f32 v[72:73], v[74:75], v[74:75], v[72:73]
	v_mov_b32_e32 v74, v33
	v_mov_b32_e32 v75, v29
	v_pk_fma_f32 v[72:73], v[74:75], v[74:75], v[72:73]
	s_nop 0
	v_add_f32_e32 v0, v72, v73
	v_add_f32_e32 v0, v0, v62
	v_add_f32_e32 v0, v0, v63
	ds_bpermute_b32 v61, v65, v0
	s_waitcnt lgkmcnt(0)
	v_add_f32_e32 v0, v0, v61
	ds_bpermute_b32 v61, v66, v0
	s_waitcnt lgkmcnt(0)
	v_add_f32_e32 v0, v0, v61
	ds_bpermute_b32 v61, v67, v0
	s_waitcnt lgkmcnt(0)
	v_add_f32_e32 v0, v0, v61
	ds_bpermute_b32 v61, v68, v0
	s_waitcnt lgkmcnt(0)
	v_add_f32_e32 v0, v0, v61
	ds_bpermute_b32 v61, v69, v0
	s_waitcnt lgkmcnt(0)
	v_add_f32_e32 v0, v0, v61
	ds_bpermute_b32 v61, v70, v0
	s_waitcnt lgkmcnt(0)
	v_add_f32_e32 v0, v0, v61
	v_fmamk_f32 v0, v0, 0x3a800000, v199
	v_cmp_gt_f32_e32 vcc, s94, v0
	v_mul_f32_e32 v61, 0x4b800000, v0
	s_nop 0
	v_cndmask_b32_e32 v0, v0, v61, vcc
	v_rsq_f32_e32 v0, v0
	s_nop 0
	v_mul_f32_e32 v61, 0x45800000, v0
	v_cndmask_b32_e32 v0, v0, v61, vcc
	s_andn2_b64 vcc, exec, s[16:17]
	s_cbranch_vccnz .LBB0_1402
	v_lshl_add_u64 v[62:63], v[58:59], 0, v[56:57]
	v_add_co_u32_e32 v76, vcc, 0x15000000, v62
	v_pk_mul_f32 v[78:79], v[30:31], v[0:1] op_sel_hi:[1,0]
	s_nop 0
	v_addc_co_u32_e32 v77, vcc, 0, v63, vcc
	global_load_dwordx2 v[88:89], v[76:77], off
	global_load_dwordx2 v[90:91], v[76:77], off offset:512
	global_load_dwordx2 v[92:93], v[76:77], off offset:1024
	global_load_dwordx2 v[94:95], v[76:77], off offset:1536
	s_waitcnt vmcnt(0)
	v_mov_b32_e32 v62, v88
	v_mov_b32_e32 v63, v89
	v_pk_mul_f32 v[82:83], v[26:27], v[0:1] op_sel_hi:[1,0]
	s_mov_b64 s[2:3], 0
	s_waitcnt vmcnt(0) lgkmcnt(0)
	v_lshlrev_b32_e32 v72, 16, v62
	v_and_b32_e32 v73, 0xffff0000, v62
	v_lshlrev_b32_e32 v74, 16, v63
	v_and_b32_e32 v75, 0xffff0000, v63
	v_pk_add_f32 v[72:73], v[10:11], v[72:73]
	v_pk_add_f32 v[74:75], v[12:13], v[74:75]
	v_pk_fma_f32 v[72:73], v[34:35], v[78:79], v[72:73]
	v_pk_mul_f32 v[78:79], v[32:33], v[0:1] op_sel_hi:[1,0]
	v_lshl_add_u64 v[62:63], v[50:51], 0, v[52:53]
	v_pk_fma_f32 v[74:75], v[78:79], v[36:37], v[74:75]
	global_store_dwordx4 v[62:63], v[72:75], off
	s_nop 1
	v_mov_b32_e32 v72, v90
	v_mov_b32_e32 v73, v91
	s_waitcnt lgkmcnt(0)
	v_lshlrev_b32_e32 v78, 16, v72
	v_and_b32_e32 v79, 0xffff0000, v72
	v_lshlrev_b32_e32 v80, 16, v73
	v_and_b32_e32 v81, 0xffff0000, v73
	v_mov_b32_e32 v72, v104
	v_mov_b32_e32 v73, v105
	v_mov_b32_e32 v74, v106
	v_mov_b32_e32 v75, v107
	v_pk_add_f32 v[78:79], v[14:15], v[78:79]
	v_pk_fma_f32 v[72:73], v[82:83], v[72:73], v[78:79]
	v_pk_add_f32 v[78:79], v[16:17], v[80:81]
	v_pk_mul_f32 v[80:81], v[28:29], v[0:1] op_sel_hi:[1,0]
	v_pk_mul_f32 v[82:83], v[22:23], v[0:1] op_sel_hi:[1,0]
	v_pk_fma_f32 v[74:75], v[80:81], v[74:75], v[78:79]
	global_store_dwordx4 v[62:63], v[72:75], off offset:1024
	s_nop 1
	v_mov_b32_e32 v72, v92
	v_mov_b32_e32 v73, v93
	s_waitcnt lgkmcnt(0)
	v_lshlrev_b32_e32 v78, 16, v72
	v_and_b32_e32 v79, 0xffff0000, v72
	v_lshlrev_b32_e32 v80, 16, v73
	v_and_b32_e32 v81, 0xffff0000, v73
	v_mov_b32_e32 v72, v108
	v_mov_b32_e32 v73, v109
	v_mov_b32_e32 v74, v110
	v_mov_b32_e32 v75, v111
	v_pk_add_f32 v[78:79], v[2:3], v[78:79]
	v_pk_fma_f32 v[72:73], v[82:83], v[72:73], v[78:79]
	v_pk_add_f32 v[78:79], v[4:5], v[80:81]
	v_pk_mul_f32 v[80:81], v[24:25], v[0:1] op_sel_hi:[1,0]
	s_nop 0
	v_pk_fma_f32 v[74:75], v[80:81], v[74:75], v[78:79]
	global_store_dwordx4 v[62:63], v[72:75], off offset:2048
	s_nop 1
	v_mov_b32_e32 v72, v94
	v_mov_b32_e32 v73, v95
	v_pk_mul_f32 v[80:81], v[18:19], v[0:1] op_sel_hi:[1,0]
	s_waitcnt lgkmcnt(0)
	v_lshlrev_b32_e32 v76, 16, v72
	v_and_b32_e32 v77, 0xffff0000, v72
	v_lshlrev_b32_e32 v78, 16, v73
	v_and_b32_e32 v79, 0xffff0000, v73
	v_mov_b32_e32 v72, v112
	v_mov_b32_e32 v73, v113
	v_mov_b32_e32 v74, v114
	v_mov_b32_e32 v75, v115
	v_pk_add_f32 v[76:77], v[6:7], v[76:77]
	v_pk_fma_f32 v[72:73], v[80:81], v[72:73], v[76:77]
	v_pk_add_f32 v[76:77], v[8:9], v[78:79]
	v_pk_mul_f32 v[78:79], v[20:21], v[0:1] op_sel_hi:[1,0]
	s_nop 0
	v_pk_fma_f32 v[74:75], v[78:79], v[74:75], v[76:77]
	global_store_dwordx4 v[62:63], v[72:75], off offset:3072
; DEVI float bf2f(bf16_t h) { return __uint_as_float(((unsigned)h) << 16); }
; DEVI unsigned pack2(float a, float b) { f2_t v = {a, b}; bf2_t r = __builtin_convertvector(v, bf2_t); return __builtin_bit_cast(unsigned, r); }
; DEVI void phase_final(const Params& p, int layer) {
;     ...
;     if (layer == 0) {
;       float ss1 = 0.f;
; #pragma unroll
;       for (int i = 0; i < 4; ++i) {
;         const float4 g = *(const float4*)(gpost + i * 256 + lane * 4);
;         uint2 o; o.x = pack2(y[i].x * rs * g.x, y[i].y * rs * g.y); o.y = pack2(y[i].z * rs * g.z, y[i].w * rs * g.w);
;         *(uint2*)(n0 + (size_t)t * 1024 + i * 256 + lane * 4) = o;
;         xv[i].x += bf2f((bf16_t)(o.x & 0xffff)); xv[i].y += bf2f((bf16_t)(o.x >> 16));
;         xv[i].z += bf2f((bf16_t)(o.y & 0xffff)); xv[i].w += bf2f((bf16_t)(o.y >> 16));
;         ss1 += xv[i].x * xv[i].x + xv[i].y * xv[i].y + xv[i].z * xv[i].z + xv[i].w * xv[i].w;
;       }
;       ss1 = wave_sum(ss1);
;       const float rs1 = rsqrtf(ss1 * (1.f / 1024.f) + 1e-6f);
; #pragma unroll
;       for (int i = 0; i < 4; ++i) {
;         const float4 g = *(const float4*)(p.norm_pre + 1024 + i * 256 + lane * 4);
;         uint2 o; o.x = pack2(xv[i].x * rs1 * g.x, xv[i].y * rs1 * g.y); o.y = pack2(xv[i].z * rs1 * g.z, xv[i].w * rs1 * g.w);
;         *(uint2*)(xb + (size_t)t * 1024 + i * 256 + lane * 4) = o;
;       }
.LBB0_1402:
	s_andn2_b64 vcc, exec, s[2:3]
	s_cbranch_vccnz .LBB0_1399
	v_pk_mul_f32 v[30:31], v[30:31], v[0:1] op_sel_hi:[1,0]
	v_lshl_add_u64 v[62:63], v[40:41], 0, v[56:57]
	v_pk_mul_f32 v[30:31], v[34:35], v[30:31]
	v_pk_mul_f32 v[26:27], v[26:27], v[0:1] op_sel_hi:[1,0]
	v_cvt_pk_bf16_f32 v34, v30, v31
	v_pk_mul_f32 v[30:31], v[32:33], v[0:1] op_sel_hi:[1,0]
	v_pk_mul_f32 v[22:23], v[22:23], v[0:1] op_sel_hi:[1,0]
	v_pk_mul_f32 v[30:31], v[30:31], v[36:37]
	v_pk_mul_f32 v[18:19], v[18:19], v[0:1] op_sel_hi:[1,0]
	v_cvt_pk_bf16_f32 v35, v30, v31
	global_store_dwordx2 v[62:63], v[34:35], off
	v_mov_b32_e32 v30, v104
	v_mov_b32_e32 v31, v105
	v_mov_b32_e32 v32, v106
	v_mov_b32_e32 v33, v107
	v_pk_mul_f32 v[26:27], v[26:27], v[30:31]
	s_nop 0
	v_cvt_pk_bf16_f32 v30, v26, v27
	v_pk_mul_f32 v[26:27], v[28:29], v[0:1] op_sel_hi:[1,0]
	s_nop 0
	v_pk_mul_f32 v[26:27], v[26:27], v[32:33]
	s_nop 0
	v_cvt_pk_bf16_f32 v31, v26, v27
	global_store_dwordx2 v[62:63], v[30:31], off offset:512
	v_mov_b32_e32 v26, v108
	v_mov_b32_e32 v27, v109
	v_mov_b32_e32 v28, v110
	v_mov_b32_e32 v29, v111
	v_pk_mul_f32 v[22:23], v[22:23], v[26:27]
	s_nop 0
	v_cvt_pk_bf16_f32 v26, v22, v23
	v_pk_mul_f32 v[22:23], v[24:25], v[0:1] op_sel_hi:[1,0]
	s_nop 0
	v_pk_mul_f32 v[22:23], v[22:23], v[28:29]
	s_nop 0
	v_cvt_pk_bf16_f32 v27, v22, v23
	global_store_dwordx2 v[62:63], v[26:27], off offset:1024
	v_mov_b32_e32 v22, v112
	v_mov_b32_e32 v23, v113
	v_mov_b32_e32 v24, v114
	v_mov_b32_e32 v25, v115
	v_pk_mul_f32 v[18:19], v[18:19], v[22:23]
	s_nop 0
	v_cvt_pk_bf16_f32 v28, v18, v19
	v_pk_mul_f32 v[18:19], v[20:21], v[0:1] op_sel_hi:[1,0]
	s_nop 0
	v_pk_mul_f32 v[18:19], v[18:19], v[24:25]
	s_nop 0
	v_cvt_pk_bf16_f32 v29, v18, v19
	global_store_dwordx2 v[62:63], v[28:29], off offset:1536
	v_and_b32_e32 v19, 0xffff0000, v35
	v_lshlrev_b32_e32 v18, 16, v35
	v_pk_add_f32 v[22:23], v[12:13], v[18:19]
	v_mov_b32_e32 v18, v116
	v_mov_b32_e32 v19, v117
	v_mov_b32_e32 v20, v118
	v_mov_b32_e32 v21, v119
	v_and_b32_e32 v13, 0xffff0000, v34
	v_lshlrev_b32_e32 v12, 16, v34
	v_pk_add_f32 v[24:25], v[10:11], v[12:13]
	v_and_b32_e32 v13, 0xffff0000, v30
	v_lshlrev_b32_e32 v12, 16, v30
	v_pk_add_f32 v[12:13], v[14:15], v[12:13]
	v_and_b32_e32 v11, 0xffff0000, v31
	v_lshlrev_b32_e32 v10, 16, v31
	v_mov_b32_e32 v32, v25
	v_mov_b32_e32 v33, v13
	v_pk_add_f32 v[10:11], v[16:17], v[10:11]
	v_mov_b32_e32 v30, v24
	v_mov_b32_e32 v31, v12
	v_pk_mul_f32 v[32:33], v[32:33], v[32:33]
	v_mov_b32_e32 v14, v22
	v_mov_b32_e32 v15, v10
	v_pk_fma_f32 v[30:31], v[30:31], v[30:31], v[32:33]
	v_mov_b32_e32 v16, v23
	v_mov_b32_e32 v17, v11
	v_pk_fma_f32 v[14:15], v[14:15], v[14:15], v[30:31]
	s_nop 0
	v_pk_fma_f32 v[30:31], v[16:17], v[16:17], v[14:15]
	v_and_b32_e32 v15, 0xffff0000, v27
	v_lshlrev_b32_e32 v14, 16, v27
	v_pk_add_f32 v[14:15], v[4:5], v[14:15]
	v_and_b32_e32 v5, 0xffff0000, v26
	v_lshlrev_b32_e32 v4, 16, v26
	v_pk_add_f32 v[16:17], v[2:3], v[4:5]
	v_and_b32_e32 v5, 0xffff0000, v28
	v_lshlrev_b32_e32 v4, 16, v28
	v_pk_add_f32 v[4:5], v[6:7], v[4:5]
	v_and_b32_e32 v3, 0xffff0000, v29
	v_lshlrev_b32_e32 v2, 16, v29
	v_mov_b32_e32 v28, v17
	v_mov_b32_e32 v29, v5
	v_pk_add_f32 v[2:3], v[8:9], v[2:3]
	v_mov_b32_e32 v26, v16
	v_mov_b32_e32 v27, v4
	v_pk_mul_f32 v[28:29], v[28:29], v[28:29]
	v_mov_b32_e32 v6, v14
	v_mov_b32_e32 v7, v2
	v_pk_fma_f32 v[26:27], v[26:27], v[26:27], v[28:29]
	v_mov_b32_e32 v8, v15
	v_mov_b32_e32 v9, v3
	v_pk_fma_f32 v[6:7], v[6:7], v[6:7], v[26:27]
	v_add_f32_e32 v0, v30, v31
	v_pk_fma_f32 v[6:7], v[8:9], v[8:9], v[6:7]
	s_nop 0
	v_add_f32_e32 v0, v0, v6
	v_add_f32_e32 v0, v0, v7
	ds_bpermute_b32 v6, v65, v0
	s_waitcnt lgkmcnt(0)
	v_add_f32_e32 v0, v0, v6
	ds_bpermute_b32 v6, v66, v0
	s_waitcnt lgkmcnt(0)
	v_add_f32_e32 v0, v0, v6
	ds_bpermute_b32 v6, v67, v0
	s_waitcnt lgkmcnt(0)
	v_add_f32_e32 v0, v0, v6
	ds_bpermute_b32 v6, v68, v0
	s_waitcnt lgkmcnt(0)
	v_add_f32_e32 v0, v0, v6
	ds_bpermute_b32 v6, v69, v0
	s_waitcnt lgkmcnt(0)
	v_add_f32_e32 v0, v0, v6
	ds_bpermute_b32 v6, v70, v0
	s_waitcnt lgkmcnt(0)
	v_add_f32_e32 v0, v0, v6
	v_fmamk_f32 v0, v0, 0x3a800000, v199
	v_cmp_gt_f32_e32 vcc, s94, v0
	v_mul_f32_e32 v6, 0x4b800000, v0
	s_nop 0
	v_cndmask_b32_e32 v0, v0, v6, vcc
	v_rsq_f32_e32 v0, v0
	s_nop 0
	v_mul_f32_e32 v6, 0x45800000, v0
	v_cndmask_b32_e32 v0, v0, v6, vcc
	v_pk_mul_f32 v[6:7], v[24:25], v[0:1] op_sel_hi:[1,0]
	v_pk_mul_f32 v[8:9], v[22:23], v[0:1] op_sel_hi:[1,0]
	v_pk_mul_f32 v[6:7], v[18:19], v[6:7]
	v_pk_mul_f32 v[8:9], v[20:21], v[8:9]
	v_add_co_u32_e32 v18, vcc, s75, v62
	v_cvt_pk_bf16_f32 v6, v6, v7
	v_cvt_pk_bf16_f32 v7, v8, v9
	v_addc_co_u32_e32 v19, vcc, 0, v63, vcc
	global_store_dwordx2 v[18:19], v[6:7], off
	v_mov_b32_e32 v6, v120
	v_mov_b32_e32 v7, v121
	v_mov_b32_e32 v8, v122
	v_mov_b32_e32 v9, v123
	v_pk_mul_f32 v[12:13], v[12:13], v[0:1] op_sel_hi:[1,0]
	v_pk_mul_f32 v[10:11], v[10:11], v[0:1] op_sel_hi:[1,0]
	v_pk_mul_f32 v[4:5], v[4:5], v[0:1] op_sel_hi:[1,0]
	v_pk_mul_f32 v[2:3], v[2:3], v[0:1] op_sel_hi:[1,0]
	v_pk_mul_f32 v[6:7], v[6:7], v[12:13]
	v_pk_mul_f32 v[8:9], v[8:9], v[10:11]
	v_cvt_pk_bf16_f32 v6, v6, v7
	v_cvt_pk_bf16_f32 v7, v8, v9
	global_store_dwordx2 v[18:19], v[6:7], off offset:512
	v_mov_b32_e32 v6, v124
	v_mov_b32_e32 v7, v125
	v_mov_b32_e32 v8, v126
	v_mov_b32_e32 v9, v127
	v_pk_mul_f32 v[10:11], v[16:17], v[0:1] op_sel_hi:[1,0]
	v_pk_mul_f32 v[6:7], v[6:7], v[10:11]
	v_pk_mul_f32 v[10:11], v[14:15], v[0:1] op_sel_hi:[1,0]
	v_cvt_pk_bf16_f32 v6, v6, v7
	v_pk_mul_f32 v[8:9], v[8:9], v[10:11]
	s_nop 0
	v_cvt_pk_bf16_f32 v7, v8, v9
	global_store_dwordx2 v[18:19], v[6:7], off offset:1024
	v_mov_b32_e32 v6, v128
	v_mov_b32_e32 v7, v129
	v_mov_b32_e32 v8, v130
	v_mov_b32_e32 v9, v131
	v_pk_mul_f32 v[4:5], v[4:5], v[6:7]
	v_pk_mul_f32 v[2:3], v[2:3], v[8:9]
	v_cvt_pk_bf16_f32 v4, v4, v5
	v_cvt_pk_bf16_f32 v5, v2, v3
	global_store_dwordx2 v[18:19], v[4:5], off offset:1536
	s_branch .LBB0_1399
